# G2 GEMM loops with s_setprio 1 around MFMA groups
# speedup vs baseline: 1.0802x; 1.0007x over previous
.Lg2_p4_loop:
	ds_read_b128 v[196:199], v223 offset:8192
	ds_read_b128 v[200:203], v223 offset:10240
	ds_read_b128 v[204:207], v223 offset:12288
	ds_read_b128 v[208:211], v223 offset:14336
	s_waitcnt lgkmcnt(4)
	s_setprio 1
	v_mfma_f32_16x16x32_bf16 v[126:129], v[212:215], v[180:183], v[126:129]
	v_mfma_f32_16x16x32_bf16 v[122:125], v[218:221], v[180:183], v[122:125]
	v_mfma_f32_16x16x32_bf16 v[118:121], v[224:227], v[180:183], v[118:121]
	v_mfma_f32_16x16x32_bf16 v[114:117], v[228:231], v[180:183], v[114:117]
	v_mfma_f32_16x16x32_bf16 v[110:113], v[212:215], v[184:187], v[110:113]
	v_mfma_f32_16x16x32_bf16 v[106:109], v[218:221], v[184:187], v[106:109]
	v_mfma_f32_16x16x32_bf16 v[102:105], v[224:227], v[184:187], v[102:105]
	v_mfma_f32_16x16x32_bf16 v[98:101], v[228:231], v[184:187], v[98:101]
	v_mfma_f32_16x16x32_bf16 v[94:97], v[212:215], v[188:191], v[94:97]
	v_mfma_f32_16x16x32_bf16 v[90:93], v[218:221], v[188:191], v[90:93]
	v_mfma_f32_16x16x32_bf16 v[86:89], v[224:227], v[188:191], v[86:89]
	v_mfma_f32_16x16x32_bf16 v[82:85], v[228:231], v[188:191], v[82:85]
	v_mfma_f32_16x16x32_bf16 v[78:81], v[212:215], v[192:195], v[78:81]
	v_mfma_f32_16x16x32_bf16 v[74:77], v[218:221], v[192:195], v[74:77]
	v_mfma_f32_16x16x32_bf16 v[70:73], v[224:227], v[192:195], v[70:73]
	v_mfma_f32_16x16x32_bf16 v[66:69], v[228:231], v[192:195], v[66:69]
	ds_read_b128 v[180:183], v248
	ds_read_b128 v[184:187], v248 offset:2048
	ds_read_b128 v[188:191], v248 offset:4096
	ds_read_b128 v[192:195], v248 offset:6144
	ds_read_b128 v[232:235], v250
	ds_read_b128 v[236:239], v250 offset:2048
	ds_read_b128 v[240:243], v250 offset:4096
	ds_read_b128 v[244:247], v250 offset:6144
	s_waitcnt lgkmcnt(8)
	v_mfma_f32_16x16x32_bf16 v[62:65], v[212:215], v[196:199], v[62:65]
	v_mfma_f32_16x16x32_bf16 v[58:61], v[218:221], v[196:199], v[58:61]
	v_mfma_f32_16x16x32_bf16 v[54:57], v[224:227], v[196:199], v[54:57]
	v_mfma_f32_16x16x32_bf16 v[50:53], v[228:231], v[196:199], v[50:53]
	v_mfma_f32_16x16x32_bf16 v[46:49], v[212:215], v[200:203], v[46:49]
	v_mfma_f32_16x16x32_bf16 v[42:45], v[218:221], v[200:203], v[42:45]
	v_mfma_f32_16x16x32_bf16 v[38:41], v[224:227], v[200:203], v[38:41]
	v_mfma_f32_16x16x32_bf16 v[34:37], v[228:231], v[200:203], v[34:37]
	v_mfma_f32_16x16x32_bf16 v[30:33], v[212:215], v[204:207], v[30:33]
	v_mfma_f32_16x16x32_bf16 v[26:29], v[218:221], v[204:207], v[26:29]
	v_mfma_f32_16x16x32_bf16 v[22:25], v[224:227], v[204:207], v[22:25]
	v_mfma_f32_16x16x32_bf16 v[18:21], v[228:231], v[204:207], v[18:21]
	v_mfma_f32_16x16x32_bf16 v[14:17], v[212:215], v[208:211], v[14:17]
	v_mfma_f32_16x16x32_bf16 v[10:13], v[218:221], v[208:211], v[10:13]
	v_mfma_f32_16x16x32_bf16 v[6:9], v[224:227], v[208:211], v[6:9]
	v_mfma_f32_16x16x32_bf16 v[2:5], v[228:231], v[208:211], v[2:5]
	ds_read_b128 v[196:199], v248 offset:8192
	ds_read_b128 v[200:203], v248 offset:10240
	ds_read_b128 v[204:207], v248 offset:12288
	ds_read_b128 v[208:211], v248 offset:14336
	s_waitcnt lgkmcnt(4)
	v_mfma_f32_16x16x32_bf16 v[126:129], v[232:235], v[180:183], v[126:129]
	v_mfma_f32_16x16x32_bf16 v[122:125], v[236:239], v[180:183], v[122:125]
	s_waitcnt vmcnt(7)
	ds_write_b128 v251, v[140:143]
	v_mfma_f32_16x16x32_bf16 v[118:121], v[240:243], v[180:183], v[118:121]
	v_mfma_f32_16x16x32_bf16 v[114:117], v[244:247], v[180:183], v[114:117]
	s_waitcnt vmcnt(6)
	ds_write_b128 v251, v[152:155] offset:8192
	v_mfma_f32_16x16x32_bf16 v[110:113], v[232:235], v[184:187], v[110:113]
	v_mfma_f32_16x16x32_bf16 v[106:109], v[236:239], v[184:187], v[106:109]
	s_waitcnt vmcnt(5)
	ds_write_b128 v251, v[156:159] offset:16384
	v_mfma_f32_16x16x32_bf16 v[102:105], v[240:243], v[184:187], v[102:105]
	v_mfma_f32_16x16x32_bf16 v[98:101], v[244:247], v[184:187], v[98:101]
	s_waitcnt vmcnt(4)
	ds_write_b128 v251, v[160:163] offset:24576
	v_mfma_f32_16x16x32_bf16 v[94:97], v[232:235], v[188:191], v[94:97]
	v_mfma_f32_16x16x32_bf16 v[90:93], v[236:239], v[188:191], v[90:93]
	s_waitcnt vmcnt(3)
	ds_write_b128 v252, v[164:167]
	v_mfma_f32_16x16x32_bf16 v[86:89], v[240:243], v[188:191], v[86:89]
	v_mfma_f32_16x16x32_bf16 v[82:85], v[244:247], v[188:191], v[82:85]
	s_waitcnt vmcnt(2)
	ds_write_b128 v252, v[168:171] offset:8192
	v_mfma_f32_16x16x32_bf16 v[78:81], v[232:235], v[192:195], v[78:81]
	v_mfma_f32_16x16x32_bf16 v[74:77], v[236:239], v[192:195], v[74:77]
	s_waitcnt vmcnt(1)
	ds_write_b128 v252, v[172:175] offset:16384
	v_mfma_f32_16x16x32_bf16 v[70:73], v[240:243], v[192:195], v[70:73]
	v_mfma_f32_16x16x32_bf16 v[66:69], v[244:247], v[192:195], v[66:69]
	s_waitcnt vmcnt(0)
	ds_write_b128 v252, v[176:179] offset:24576
	s_setprio 0
	s_waitcnt lgkmcnt(0)
	s_barrier
	s_add_u32 s8, s8, 0x80
	s_addc_u32 s9, s9, 0
	s_cmpk_eq_i32 s8, 0x780
	s_cbranch_scc1 .Lg2_p4_tail
	v_xor_b32_e32 v223, 0x8000, v223
	v_xor_b32_e32 v249, 0x8000, v249
	v_xor_b32_e32 v248, 0x8000, v248
	v_xor_b32_e32 v250, 0x8000, v250
	v_xor_b32_e32 v251, 0x8000, v251
	v_xor_b32_e32 v252, 0x8000, v252
	ds_read_b128 v[180:183], v223
	ds_read_b128 v[184:187], v223 offset:2048
	ds_read_b128 v[188:191], v223 offset:4096
	ds_read_b128 v[192:195], v223 offset:6144
	ds_read_b128 v[212:215], v249
	ds_read_b128 v[218:221], v249 offset:2048
	ds_read_b128 v[224:227], v249 offset:4096
	ds_read_b128 v[228:231], v249 offset:6144
	s_setprio 1
	v_mfma_f32_16x16x32_bf16 v[62:65], v[232:235], v[196:199], v[62:65]
	v_lshl_add_u64 v[140:141], v[136:137], 0, s[8:9]
	v_add_co_u32_e32 v142, vcc, s15, v140
	v_mfma_f32_16x16x32_bf16 v[58:61], v[236:239], v[196:199], v[58:61]
	s_nop 1
	v_addc_co_u32_e32 v143, vcc, 0, v141, vcc
	v_mfma_f32_16x16x32_bf16 v[54:57], v[240:243], v[196:199], v[54:57]
	v_add_co_u32_e32 v144, vcc, s16, v140
	s_nop 1
	v_mfma_f32_16x16x32_bf16 v[50:53], v[244:247], v[196:199], v[50:53]
	v_addc_co_u32_e32 v145, vcc, 0, v141, vcc
	v_add_co_u32_e32 v156, vcc, s17, v140
	v_mfma_f32_16x16x32_bf16 v[46:49], v[232:235], v[200:203], v[46:49]
	s_nop 1
	v_addc_co_u32_e32 v157, vcc, 0, v141, vcc
	v_mfma_f32_16x16x32_bf16 v[42:45], v[236:239], v[200:203], v[42:45]
	v_add_co_u32_e32 v160, vcc, s28, v140
	s_nop 1
	v_mfma_f32_16x16x32_bf16 v[38:41], v[240:243], v[200:203], v[38:41]
	v_addc_co_u32_e32 v161, vcc, 0, v141, vcc
	global_load_dwordx4 v[140:143], v[142:143], off offset:128
	v_mfma_f32_16x16x32_bf16 v[34:37], v[244:247], v[200:203], v[34:37]
	global_load_dwordx4 v[152:155], v[144:145], off offset:128
	global_load_dwordx4 v[156:159], v[156:157], off offset:128
	global_load_dwordx4 v[160:163], v[160:161], off offset:128
	v_mfma_f32_16x16x32_bf16 v[30:33], v[232:235], v[204:207], v[30:33]
	v_lshl_add_u64 v[144:145], v[138:139], 0, s[8:9]
	v_add_co_u32_e32 v164, vcc, s29, v144
	v_mfma_f32_16x16x32_bf16 v[26:29], v[236:239], v[204:207], v[26:29]
	s_nop 1
	v_addc_co_u32_e32 v165, vcc, 0, v145, vcc
	v_mfma_f32_16x16x32_bf16 v[22:25], v[240:243], v[204:207], v[22:25]
	v_add_co_u32_e32 v168, vcc, s38, v144
	s_nop 1
	v_mfma_f32_16x16x32_bf16 v[18:21], v[244:247], v[204:207], v[18:21]
	v_addc_co_u32_e32 v169, vcc, 0, v145, vcc
	v_add_co_u32_e32 v172, vcc, s39, v144
	v_mfma_f32_16x16x32_bf16 v[14:17], v[232:235], v[208:211], v[14:17]
	s_nop 1
	v_addc_co_u32_e32 v173, vcc, 0, v145, vcc
	v_mfma_f32_16x16x32_bf16 v[10:13], v[236:239], v[208:211], v[10:13]
	v_add_co_u32_e32 v144, vcc, s42, v144
	s_nop 1
	v_mfma_f32_16x16x32_bf16 v[6:9], v[240:243], v[208:211], v[6:9]
	v_addc_co_u32_e32 v145, vcc, 0, v145, vcc
	global_load_dwordx4 v[164:167], v[164:165], off offset:128
	v_mfma_f32_16x16x32_bf16 v[2:5], v[244:247], v[208:211], v[2:5]
	global_load_dwordx4 v[168:171], v[168:169], off offset:128
	global_load_dwordx4 v[172:175], v[172:173], off offset:128
	global_load_dwordx4 v[176:179], v[144:145], off offset:128
	s_setprio 0
	s_branch .Lg2_p4_loop

.Lg2_p6_loop:
	ds_read_b128 v[198:201], v214 offset:8192
	ds_read_b128 v[202:205], v214 offset:10240
	ds_read_b128 v[206:209], v214 offset:12288
	ds_read_b128 v[210:213], v214 offset:14336
	s_waitcnt lgkmcnt(4)
	s_setprio 1
	v_mfma_f32_16x16x32_bf16 v[126:129], v[218:221], v[182:185], v[126:129]
	v_mfma_f32_16x16x32_bf16 v[122:125], v[224:227], v[182:185], v[122:125]
	v_mfma_f32_16x16x32_bf16 v[118:121], v[228:231], v[182:185], v[118:121]
	v_mfma_f32_16x16x32_bf16 v[114:117], v[232:235], v[182:185], v[114:117]
	v_mfma_f32_16x16x32_bf16 v[110:113], v[218:221], v[186:189], v[110:113]
	v_mfma_f32_16x16x32_bf16 v[106:109], v[224:227], v[186:189], v[106:109]
	v_mfma_f32_16x16x32_bf16 v[102:105], v[228:231], v[186:189], v[102:105]
	v_mfma_f32_16x16x32_bf16 v[98:101], v[232:235], v[186:189], v[98:101]
	v_mfma_f32_16x16x32_bf16 v[94:97], v[218:221], v[190:193], v[94:97]
	v_mfma_f32_16x16x32_bf16 v[90:93], v[224:227], v[190:193], v[90:93]
	v_mfma_f32_16x16x32_bf16 v[86:89], v[228:231], v[190:193], v[86:89]
	v_mfma_f32_16x16x32_bf16 v[82:85], v[232:235], v[190:193], v[82:85]
	v_mfma_f32_16x16x32_bf16 v[78:81], v[218:221], v[194:197], v[78:81]
	v_mfma_f32_16x16x32_bf16 v[74:77], v[224:227], v[194:197], v[74:77]
	v_mfma_f32_16x16x32_bf16 v[70:73], v[228:231], v[194:197], v[70:73]
	v_mfma_f32_16x16x32_bf16 v[66:69], v[232:235], v[194:197], v[66:69]
	ds_read_b128 v[182:185], v215
	ds_read_b128 v[186:189], v215 offset:2048
	ds_read_b128 v[190:193], v215 offset:4096
	ds_read_b128 v[194:197], v215 offset:6144
	ds_read_b128 v[236:239], v252
	ds_read_b128 v[240:243], v252 offset:2048
	ds_read_b128 v[244:247], v252 offset:4096
	ds_read_b128 v[248:251], v252 offset:6144
	s_waitcnt lgkmcnt(8)
	v_mfma_f32_16x16x32_bf16 v[62:65], v[218:221], v[198:201], v[62:65]
	v_mfma_f32_16x16x32_bf16 v[58:61], v[224:227], v[198:201], v[58:61]
	v_mfma_f32_16x16x32_bf16 v[54:57], v[228:231], v[198:201], v[54:57]
	v_mfma_f32_16x16x32_bf16 v[50:53], v[232:235], v[198:201], v[50:53]
	v_mfma_f32_16x16x32_bf16 v[46:49], v[218:221], v[202:205], v[46:49]
	v_mfma_f32_16x16x32_bf16 v[42:45], v[224:227], v[202:205], v[42:45]
	v_mfma_f32_16x16x32_bf16 v[38:41], v[228:231], v[202:205], v[38:41]
	v_mfma_f32_16x16x32_bf16 v[34:37], v[232:235], v[202:205], v[34:37]
	v_mfma_f32_16x16x32_bf16 v[30:33], v[218:221], v[206:209], v[30:33]
	v_mfma_f32_16x16x32_bf16 v[26:29], v[224:227], v[206:209], v[26:29]
	v_mfma_f32_16x16x32_bf16 v[22:25], v[228:231], v[206:209], v[22:25]
	v_mfma_f32_16x16x32_bf16 v[18:21], v[232:235], v[206:209], v[18:21]
	v_mfma_f32_16x16x32_bf16 v[14:17], v[218:221], v[210:213], v[14:17]
	v_mfma_f32_16x16x32_bf16 v[10:13], v[224:227], v[210:213], v[10:13]
	v_mfma_f32_16x16x32_bf16 v[6:9], v[228:231], v[210:213], v[6:9]
	v_mfma_f32_16x16x32_bf16 v[2:5], v[232:235], v[210:213], v[2:5]
	ds_read_b128 v[198:201], v215 offset:8192
	ds_read_b128 v[202:205], v215 offset:10240
	ds_read_b128 v[206:209], v215 offset:12288
	ds_read_b128 v[210:213], v215 offset:14336
	s_waitcnt lgkmcnt(4)
	v_mfma_f32_16x16x32_bf16 v[126:129], v[236:239], v[182:185], v[126:129]
	v_mfma_f32_16x16x32_bf16 v[122:125], v[240:243], v[182:185], v[122:125]
	s_waitcnt vmcnt(7)
	ds_write_b128 v253, v[150:153]
	v_mfma_f32_16x16x32_bf16 v[118:121], v[244:247], v[182:185], v[118:121]
	v_mfma_f32_16x16x32_bf16 v[114:117], v[248:251], v[182:185], v[114:117]
	s_waitcnt vmcnt(6)
	ds_write_b128 v253, v[154:157] offset:8192
	v_mfma_f32_16x16x32_bf16 v[110:113], v[236:239], v[186:189], v[110:113]
	v_mfma_f32_16x16x32_bf16 v[106:109], v[240:243], v[186:189], v[106:109]
	s_waitcnt vmcnt(5)
	ds_write_b128 v253, v[158:161] offset:16384
	v_mfma_f32_16x16x32_bf16 v[102:105], v[244:247], v[186:189], v[102:105]
	v_mfma_f32_16x16x32_bf16 v[98:101], v[248:251], v[186:189], v[98:101]
	s_waitcnt vmcnt(4)
	ds_write_b128 v253, v[162:165] offset:24576
	v_mfma_f32_16x16x32_bf16 v[94:97], v[236:239], v[190:193], v[94:97]
	v_mfma_f32_16x16x32_bf16 v[90:93], v[240:243], v[190:193], v[90:93]
	s_waitcnt vmcnt(3)
	ds_write_b128 v254, v[166:169]
	v_mfma_f32_16x16x32_bf16 v[86:89], v[244:247], v[190:193], v[86:89]
	v_mfma_f32_16x16x32_bf16 v[82:85], v[248:251], v[190:193], v[82:85]
	s_waitcnt vmcnt(2)
	ds_write_b128 v254, v[170:173] offset:8192
	v_mfma_f32_16x16x32_bf16 v[78:81], v[236:239], v[194:197], v[78:81]
	v_mfma_f32_16x16x32_bf16 v[74:77], v[240:243], v[194:197], v[74:77]
	s_waitcnt vmcnt(1)
	ds_write_b128 v254, v[174:177] offset:16384
	v_mfma_f32_16x16x32_bf16 v[70:73], v[244:247], v[194:197], v[70:73]
	v_mfma_f32_16x16x32_bf16 v[66:69], v[248:251], v[194:197], v[66:69]
	s_waitcnt vmcnt(0)
	ds_write_b128 v254, v[178:181] offset:24576
	s_setprio 0
	s_waitcnt lgkmcnt(0)
	s_barrier
	s_add_u32 s0, s0, 0x80
	s_addc_u32 s1, s1, 0
	s_cmpk_eq_i32 s0, 0x780
	s_cbranch_scc1 .Lg2_p6_tail
	v_xor_b32_e32 v214, 0x8000, v214
	v_xor_b32_e32 v223, 0x8000, v223
	v_xor_b32_e32 v215, 0x8000, v215
	v_xor_b32_e32 v252, 0x8000, v252
	v_xor_b32_e32 v253, 0x8000, v253
	v_xor_b32_e32 v254, 0x8000, v254
	ds_read_b128 v[182:185], v214
	ds_read_b128 v[186:189], v214 offset:2048
	ds_read_b128 v[190:193], v214 offset:4096
	ds_read_b128 v[194:197], v214 offset:6144
	ds_read_b128 v[218:221], v223
	ds_read_b128 v[224:227], v223 offset:2048
	ds_read_b128 v[228:231], v223 offset:4096
	ds_read_b128 v[232:235], v223 offset:6144
	s_setprio 1
	v_mfma_f32_16x16x32_bf16 v[62:65], v[236:239], v[198:201], v[62:65]
	v_lshl_add_u64 v[150:151], v[142:143], 0, s[0:1]
	v_add_co_u32_e32 v152, vcc, s12, v150
	v_mfma_f32_16x16x32_bf16 v[58:61], v[240:243], v[198:201], v[58:61]
	s_nop 1
	v_addc_co_u32_e32 v153, vcc, 0, v151, vcc
	v_mfma_f32_16x16x32_bf16 v[54:57], v[244:247], v[198:201], v[54:57]
	v_add_co_u32_e32 v154, vcc, s13, v150
	s_nop 1
	v_mfma_f32_16x16x32_bf16 v[50:53], v[248:251], v[198:201], v[50:53]
	v_addc_co_u32_e32 v155, vcc, 0, v151, vcc
	v_add_co_u32_e32 v158, vcc, s14, v150
	v_mfma_f32_16x16x32_bf16 v[46:49], v[236:239], v[202:205], v[46:49]
	s_nop 1
	v_addc_co_u32_e32 v159, vcc, 0, v151, vcc
	v_mfma_f32_16x16x32_bf16 v[42:45], v[240:243], v[202:205], v[42:45]
	v_add_co_u32_e32 v162, vcc, s15, v150
	s_nop 1
	v_mfma_f32_16x16x32_bf16 v[38:41], v[244:247], v[202:205], v[38:41]
	v_addc_co_u32_e32 v163, vcc, 0, v151, vcc
	global_load_dwordx4 v[150:153], v[152:153], off offset:128
	v_mfma_f32_16x16x32_bf16 v[34:37], v[248:251], v[202:205], v[34:37]
	global_load_dwordx4 v[154:157], v[154:155], off offset:128
	global_load_dwordx4 v[158:161], v[158:159], off offset:128
	global_load_dwordx4 v[162:165], v[162:163], off offset:128
	v_mfma_f32_16x16x32_bf16 v[30:33], v[236:239], v[206:209], v[30:33]
	v_lshl_add_u64 v[174:175], v[140:141], 0, s[0:1]
	v_add_co_u32_e32 v166, vcc, s16, v174
	v_mfma_f32_16x16x32_bf16 v[26:29], v[240:243], v[206:209], v[26:29]
	s_nop 1
	v_addc_co_u32_e32 v167, vcc, 0, v175, vcc
	v_mfma_f32_16x16x32_bf16 v[22:25], v[244:247], v[206:209], v[22:25]
	v_add_co_u32_e32 v170, vcc, s17, v174
	s_nop 1
	v_mfma_f32_16x16x32_bf16 v[18:21], v[248:251], v[206:209], v[18:21]
	v_addc_co_u32_e32 v171, vcc, 0, v175, vcc
	v_add_co_u32_e32 v176, vcc, s28, v174
	v_mfma_f32_16x16x32_bf16 v[14:17], v[236:239], v[210:213], v[14:17]
	s_nop 1
	v_addc_co_u32_e32 v177, vcc, 0, v175, vcc
	v_mfma_f32_16x16x32_bf16 v[10:13], v[240:243], v[210:213], v[10:13]
	v_add_co_u32_e32 v178, vcc, s29, v174
	s_nop 1
	v_mfma_f32_16x16x32_bf16 v[6:9], v[244:247], v[210:213], v[6:9]
	v_addc_co_u32_e32 v179, vcc, 0, v175, vcc
	global_load_dwordx4 v[166:169], v[166:167], off offset:128
	v_mfma_f32_16x16x32_bf16 v[2:5], v[248:251], v[210:213], v[2:5]
	global_load_dwordx4 v[170:173], v[170:171], off offset:128
	global_load_dwordx4 v[174:177], v[176:177], off offset:128
	global_load_dwordx4 v[178:181], v[178:179], off offset:128
	s_setprio 0
	s_branch .Lg2_p6_loop

.Lg2_p7_loop:
	ds_read_b128 v[196:199], v223 offset:8192
	ds_read_b128 v[200:203], v223 offset:10240
	ds_read_b128 v[204:207], v223 offset:12288
	ds_read_b128 v[208:211], v223 offset:14336
	s_waitcnt lgkmcnt(4)
	s_setprio 1
	v_mfma_f32_16x16x32_bf16 v[126:129], v[212:215], v[180:183], v[126:129]
	v_mfma_f32_16x16x32_bf16 v[122:125], v[218:221], v[180:183], v[122:125]
	v_mfma_f32_16x16x32_bf16 v[118:121], v[224:227], v[180:183], v[118:121]
	v_mfma_f32_16x16x32_bf16 v[114:117], v[228:231], v[180:183], v[114:117]
	v_mfma_f32_16x16x32_bf16 v[110:113], v[212:215], v[184:187], v[110:113]
	v_mfma_f32_16x16x32_bf16 v[106:109], v[218:221], v[184:187], v[106:109]
	v_mfma_f32_16x16x32_bf16 v[102:105], v[224:227], v[184:187], v[102:105]
	v_mfma_f32_16x16x32_bf16 v[98:101], v[228:231], v[184:187], v[98:101]
	v_mfma_f32_16x16x32_bf16 v[94:97], v[212:215], v[188:191], v[94:97]
	v_mfma_f32_16x16x32_bf16 v[90:93], v[218:221], v[188:191], v[90:93]
	v_mfma_f32_16x16x32_bf16 v[86:89], v[224:227], v[188:191], v[86:89]
	v_mfma_f32_16x16x32_bf16 v[82:85], v[228:231], v[188:191], v[82:85]
	v_mfma_f32_16x16x32_bf16 v[78:81], v[212:215], v[192:195], v[78:81]
	v_mfma_f32_16x16x32_bf16 v[74:77], v[218:221], v[192:195], v[74:77]
	v_mfma_f32_16x16x32_bf16 v[70:73], v[224:227], v[192:195], v[70:73]
	v_mfma_f32_16x16x32_bf16 v[66:69], v[228:231], v[192:195], v[66:69]
	ds_read_b128 v[180:183], v248
	ds_read_b128 v[184:187], v248 offset:2048
	ds_read_b128 v[188:191], v248 offset:4096
	ds_read_b128 v[192:195], v248 offset:6144
	ds_read_b128 v[232:235], v250
	ds_read_b128 v[236:239], v250 offset:2048
	ds_read_b128 v[240:243], v250 offset:4096
	ds_read_b128 v[244:247], v250 offset:6144
	s_waitcnt lgkmcnt(8)
	v_mfma_f32_16x16x32_bf16 v[62:65], v[212:215], v[196:199], v[62:65]
	v_mfma_f32_16x16x32_bf16 v[58:61], v[218:221], v[196:199], v[58:61]
	v_mfma_f32_16x16x32_bf16 v[54:57], v[224:227], v[196:199], v[54:57]
	v_mfma_f32_16x16x32_bf16 v[50:53], v[228:231], v[196:199], v[50:53]
	v_mfma_f32_16x16x32_bf16 v[46:49], v[212:215], v[200:203], v[46:49]
	v_mfma_f32_16x16x32_bf16 v[42:45], v[218:221], v[200:203], v[42:45]
	v_mfma_f32_16x16x32_bf16 v[38:41], v[224:227], v[200:203], v[38:41]
	v_mfma_f32_16x16x32_bf16 v[34:37], v[228:231], v[200:203], v[34:37]
	v_mfma_f32_16x16x32_bf16 v[30:33], v[212:215], v[204:207], v[30:33]
	v_mfma_f32_16x16x32_bf16 v[26:29], v[218:221], v[204:207], v[26:29]
	v_mfma_f32_16x16x32_bf16 v[22:25], v[224:227], v[204:207], v[22:25]
	v_mfma_f32_16x16x32_bf16 v[18:21], v[228:231], v[204:207], v[18:21]
	v_mfma_f32_16x16x32_bf16 v[14:17], v[212:215], v[208:211], v[14:17]
	v_mfma_f32_16x16x32_bf16 v[10:13], v[218:221], v[208:211], v[10:13]
	v_mfma_f32_16x16x32_bf16 v[6:9], v[224:227], v[208:211], v[6:9]
	v_mfma_f32_16x16x32_bf16 v[2:5], v[228:231], v[208:211], v[2:5]
	ds_read_b128 v[196:199], v248 offset:8192
	ds_read_b128 v[200:203], v248 offset:10240
	ds_read_b128 v[204:207], v248 offset:12288
	ds_read_b128 v[208:211], v248 offset:14336
	s_waitcnt lgkmcnt(4)
	v_mfma_f32_16x16x32_bf16 v[126:129], v[232:235], v[180:183], v[126:129]
	v_mfma_f32_16x16x32_bf16 v[122:125], v[236:239], v[180:183], v[122:125]
	s_waitcnt vmcnt(7)
	ds_write_b128 v251, v[140:143]
	v_mfma_f32_16x16x32_bf16 v[118:121], v[240:243], v[180:183], v[118:121]
	v_mfma_f32_16x16x32_bf16 v[114:117], v[244:247], v[180:183], v[114:117]
	s_waitcnt vmcnt(6)
	ds_write_b128 v251, v[152:155] offset:8192
	v_mfma_f32_16x16x32_bf16 v[110:113], v[232:235], v[184:187], v[110:113]
	v_mfma_f32_16x16x32_bf16 v[106:109], v[236:239], v[184:187], v[106:109]
	s_waitcnt vmcnt(5)
	ds_write_b128 v251, v[156:159] offset:16384
	v_mfma_f32_16x16x32_bf16 v[102:105], v[240:243], v[184:187], v[102:105]
	v_mfma_f32_16x16x32_bf16 v[98:101], v[244:247], v[184:187], v[98:101]
	s_waitcnt vmcnt(4)
	ds_write_b128 v251, v[160:163] offset:24576
	v_mfma_f32_16x16x32_bf16 v[94:97], v[232:235], v[188:191], v[94:97]
	v_mfma_f32_16x16x32_bf16 v[90:93], v[236:239], v[188:191], v[90:93]
	s_waitcnt vmcnt(3)
	ds_write_b128 v252, v[164:167]
	v_mfma_f32_16x16x32_bf16 v[86:89], v[240:243], v[188:191], v[86:89]
	v_mfma_f32_16x16x32_bf16 v[82:85], v[244:247], v[188:191], v[82:85]
	s_waitcnt vmcnt(2)
	ds_write_b128 v252, v[168:171] offset:8192
	v_mfma_f32_16x16x32_bf16 v[78:81], v[232:235], v[192:195], v[78:81]
	v_mfma_f32_16x16x32_bf16 v[74:77], v[236:239], v[192:195], v[74:77]
	s_waitcnt vmcnt(1)
	ds_write_b128 v252, v[172:175] offset:16384
	v_mfma_f32_16x16x32_bf16 v[70:73], v[240:243], v[192:195], v[70:73]
	v_mfma_f32_16x16x32_bf16 v[66:69], v[244:247], v[192:195], v[66:69]
	s_waitcnt vmcnt(0)
	ds_write_b128 v252, v[176:179] offset:24576
	s_setprio 0
	s_waitcnt lgkmcnt(0)
	s_barrier
	s_add_u32 s8, s8, 0x80
	s_addc_u32 s9, s9, 0
	s_cmpk_eq_i32 s8, 0x1580
	s_cbranch_scc1 .Lg2_p7_tail
	v_xor_b32_e32 v223, 0x8000, v223
	v_xor_b32_e32 v249, 0x8000, v249
	v_xor_b32_e32 v248, 0x8000, v248
	v_xor_b32_e32 v250, 0x8000, v250
	v_xor_b32_e32 v251, 0x8000, v251
	v_xor_b32_e32 v252, 0x8000, v252
	ds_read_b128 v[180:183], v223
	ds_read_b128 v[184:187], v223 offset:2048
	ds_read_b128 v[188:191], v223 offset:4096
	ds_read_b128 v[192:195], v223 offset:6144
	ds_read_b128 v[212:215], v249
	ds_read_b128 v[218:221], v249 offset:2048
	ds_read_b128 v[224:227], v249 offset:4096
	ds_read_b128 v[228:231], v249 offset:6144
	s_setprio 1
	v_mfma_f32_16x16x32_bf16 v[62:65], v[232:235], v[196:199], v[62:65]
	v_lshl_add_u64 v[140:141], v[136:137], 0, s[8:9]
	v_add_co_u32_e32 v142, vcc, s16, v140
	v_mfma_f32_16x16x32_bf16 v[58:61], v[236:239], v[196:199], v[58:61]
	s_nop 1
	v_addc_co_u32_e32 v143, vcc, 0, v141, vcc
	v_mfma_f32_16x16x32_bf16 v[54:57], v[240:243], v[196:199], v[54:57]
	v_add_co_u32_e32 v144, vcc, s17, v140
	s_nop 1
	v_mfma_f32_16x16x32_bf16 v[50:53], v[244:247], v[196:199], v[50:53]
	v_addc_co_u32_e32 v145, vcc, 0, v141, vcc
	v_add_co_u32_e32 v156, vcc, s28, v140
	v_mfma_f32_16x16x32_bf16 v[46:49], v[232:235], v[200:203], v[46:49]
	s_nop 1
	v_addc_co_u32_e32 v157, vcc, 0, v141, vcc
	v_mfma_f32_16x16x32_bf16 v[42:45], v[236:239], v[200:203], v[42:45]
	v_add_co_u32_e32 v160, vcc, s29, v140
	s_nop 1
	v_mfma_f32_16x16x32_bf16 v[38:41], v[240:243], v[200:203], v[38:41]
	v_addc_co_u32_e32 v161, vcc, 0, v141, vcc
	global_load_dwordx4 v[140:143], v[142:143], off offset:128
	v_mfma_f32_16x16x32_bf16 v[34:37], v[244:247], v[200:203], v[34:37]
	global_load_dwordx4 v[152:155], v[144:145], off offset:128
	global_load_dwordx4 v[156:159], v[156:157], off offset:128
	global_load_dwordx4 v[160:163], v[160:161], off offset:128
	v_mfma_f32_16x16x32_bf16 v[30:33], v[232:235], v[204:207], v[30:33]
	v_lshl_add_u64 v[144:145], v[138:139], 0, s[8:9]
	v_add_co_u32_e32 v164, vcc, s36, v144
	v_mfma_f32_16x16x32_bf16 v[26:29], v[236:239], v[204:207], v[26:29]
	s_nop 1
	v_addc_co_u32_e32 v165, vcc, 0, v145, vcc
	v_mfma_f32_16x16x32_bf16 v[22:25], v[240:243], v[204:207], v[22:25]
	v_add_co_u32_e32 v168, vcc, s37, v144
	s_nop 1
	v_mfma_f32_16x16x32_bf16 v[18:21], v[244:247], v[204:207], v[18:21]
	v_addc_co_u32_e32 v169, vcc, 0, v145, vcc
	v_add_co_u32_e32 v172, vcc, s38, v144
	v_mfma_f32_16x16x32_bf16 v[14:17], v[232:235], v[208:211], v[14:17]
	s_nop 1
	v_addc_co_u32_e32 v173, vcc, 0, v145, vcc
	v_mfma_f32_16x16x32_bf16 v[10:13], v[236:239], v[208:211], v[10:13]
	v_add_co_u32_e32 v144, vcc, s39, v144
	s_nop 1
	v_mfma_f32_16x16x32_bf16 v[6:9], v[240:243], v[208:211], v[6:9]
	v_addc_co_u32_e32 v145, vcc, 0, v145, vcc
	global_load_dwordx4 v[164:167], v[164:165], off offset:128
	v_mfma_f32_16x16x32_bf16 v[2:5], v[244:247], v[208:211], v[2:5]
	global_load_dwordx4 v[168:171], v[168:169], off offset:128
	global_load_dwordx4 v[172:175], v[172:173], off offset:128
	global_load_dwordx4 v[176:179], v[144:145], off offset:128
	s_setprio 0
	s_branch .Lg2_p7_loop

.Lg2_p12_loop:
	ds_read_b128 v[196:199], v223 offset:8192
	ds_read_b128 v[200:203], v223 offset:10240
	ds_read_b128 v[204:207], v223 offset:12288
	ds_read_b128 v[208:211], v223 offset:14336
	s_waitcnt lgkmcnt(4)
	s_setprio 1
	v_mfma_f32_16x16x32_bf16 v[126:129], v[212:215], v[180:183], v[126:129]
	v_mfma_f32_16x16x32_bf16 v[122:125], v[218:221], v[180:183], v[122:125]
	v_mfma_f32_16x16x32_bf16 v[118:121], v[224:227], v[180:183], v[118:121]
	v_mfma_f32_16x16x32_bf16 v[114:117], v[228:231], v[180:183], v[114:117]
	v_mfma_f32_16x16x32_bf16 v[110:113], v[212:215], v[184:187], v[110:113]
	v_mfma_f32_16x16x32_bf16 v[106:109], v[218:221], v[184:187], v[106:109]
	v_mfma_f32_16x16x32_bf16 v[102:105], v[224:227], v[184:187], v[102:105]
	v_mfma_f32_16x16x32_bf16 v[98:101], v[228:231], v[184:187], v[98:101]
	v_mfma_f32_16x16x32_bf16 v[94:97], v[212:215], v[188:191], v[94:97]
	v_mfma_f32_16x16x32_bf16 v[90:93], v[218:221], v[188:191], v[90:93]
	v_mfma_f32_16x16x32_bf16 v[86:89], v[224:227], v[188:191], v[86:89]
	v_mfma_f32_16x16x32_bf16 v[82:85], v[228:231], v[188:191], v[82:85]
	v_mfma_f32_16x16x32_bf16 v[78:81], v[212:215], v[192:195], v[78:81]
	v_mfma_f32_16x16x32_bf16 v[74:77], v[218:221], v[192:195], v[74:77]
	v_mfma_f32_16x16x32_bf16 v[70:73], v[224:227], v[192:195], v[70:73]
	v_mfma_f32_16x16x32_bf16 v[66:69], v[228:231], v[192:195], v[66:69]
	ds_read_b128 v[180:183], v248
	ds_read_b128 v[184:187], v248 offset:2048
	ds_read_b128 v[188:191], v248 offset:4096
	ds_read_b128 v[192:195], v248 offset:6144
	ds_read_b128 v[232:235], v250
	ds_read_b128 v[236:239], v250 offset:2048
	ds_read_b128 v[240:243], v250 offset:4096
	ds_read_b128 v[244:247], v250 offset:6144
	s_waitcnt lgkmcnt(8)
	v_mfma_f32_16x16x32_bf16 v[62:65], v[212:215], v[196:199], v[62:65]
	v_mfma_f32_16x16x32_bf16 v[58:61], v[218:221], v[196:199], v[58:61]
	v_mfma_f32_16x16x32_bf16 v[54:57], v[224:227], v[196:199], v[54:57]
	v_mfma_f32_16x16x32_bf16 v[50:53], v[228:231], v[196:199], v[50:53]
	v_mfma_f32_16x16x32_bf16 v[46:49], v[212:215], v[200:203], v[46:49]
	v_mfma_f32_16x16x32_bf16 v[42:45], v[218:221], v[200:203], v[42:45]
	v_mfma_f32_16x16x32_bf16 v[38:41], v[224:227], v[200:203], v[38:41]
	v_mfma_f32_16x16x32_bf16 v[34:37], v[228:231], v[200:203], v[34:37]
	v_mfma_f32_16x16x32_bf16 v[30:33], v[212:215], v[204:207], v[30:33]
	v_mfma_f32_16x16x32_bf16 v[26:29], v[218:221], v[204:207], v[26:29]
	v_mfma_f32_16x16x32_bf16 v[22:25], v[224:227], v[204:207], v[22:25]
	v_mfma_f32_16x16x32_bf16 v[18:21], v[228:231], v[204:207], v[18:21]
	v_mfma_f32_16x16x32_bf16 v[14:17], v[212:215], v[208:211], v[14:17]
	v_mfma_f32_16x16x32_bf16 v[10:13], v[218:221], v[208:211], v[10:13]
	v_mfma_f32_16x16x32_bf16 v[6:9], v[224:227], v[208:211], v[6:9]
	v_mfma_f32_16x16x32_bf16 v[2:5], v[228:231], v[208:211], v[2:5]
	ds_read_b128 v[196:199], v248 offset:8192
	ds_read_b128 v[200:203], v248 offset:10240
	ds_read_b128 v[204:207], v248 offset:12288
	ds_read_b128 v[208:211], v248 offset:14336
	s_waitcnt lgkmcnt(4)
	v_mfma_f32_16x16x32_bf16 v[126:129], v[232:235], v[180:183], v[126:129]
	v_mfma_f32_16x16x32_bf16 v[122:125], v[236:239], v[180:183], v[122:125]
	s_waitcnt vmcnt(7)
	ds_write_b128 v251, v[140:143]
	v_mfma_f32_16x16x32_bf16 v[118:121], v[240:243], v[180:183], v[118:121]
	v_mfma_f32_16x16x32_bf16 v[114:117], v[244:247], v[180:183], v[114:117]
	s_waitcnt vmcnt(6)
	ds_write_b128 v251, v[152:155] offset:8192
	v_mfma_f32_16x16x32_bf16 v[110:113], v[232:235], v[184:187], v[110:113]
	v_mfma_f32_16x16x32_bf16 v[106:109], v[236:239], v[184:187], v[106:109]
	s_waitcnt vmcnt(5)
	ds_write_b128 v251, v[156:159] offset:16384
	v_mfma_f32_16x16x32_bf16 v[102:105], v[240:243], v[184:187], v[102:105]
	v_mfma_f32_16x16x32_bf16 v[98:101], v[244:247], v[184:187], v[98:101]
	s_waitcnt vmcnt(4)
	ds_write_b128 v251, v[160:163] offset:24576
	v_mfma_f32_16x16x32_bf16 v[94:97], v[232:235], v[188:191], v[94:97]
	v_mfma_f32_16x16x32_bf16 v[90:93], v[236:239], v[188:191], v[90:93]
	s_waitcnt vmcnt(3)
	ds_write_b128 v252, v[164:167]
	v_mfma_f32_16x16x32_bf16 v[86:89], v[240:243], v[188:191], v[86:89]
	v_mfma_f32_16x16x32_bf16 v[82:85], v[244:247], v[188:191], v[82:85]
	s_waitcnt vmcnt(2)
	ds_write_b128 v252, v[168:171] offset:8192
	v_mfma_f32_16x16x32_bf16 v[78:81], v[232:235], v[192:195], v[78:81]
	v_mfma_f32_16x16x32_bf16 v[74:77], v[236:239], v[192:195], v[74:77]
	s_waitcnt vmcnt(1)
	ds_write_b128 v252, v[172:175] offset:16384
	v_mfma_f32_16x16x32_bf16 v[70:73], v[240:243], v[192:195], v[70:73]
	v_mfma_f32_16x16x32_bf16 v[66:69], v[244:247], v[192:195], v[66:69]
	s_waitcnt vmcnt(0)
	ds_write_b128 v252, v[176:179] offset:24576
	s_setprio 0
	s_waitcnt lgkmcnt(0)
	s_barrier
	s_add_u32 s8, s8, 0x80
	s_addc_u32 s9, s9, 0
	s_cmpk_eq_i32 s8, 0x780
	s_cbranch_scc1 .Lg2_p12_tail
	v_xor_b32_e32 v223, 0x8000, v223
	v_xor_b32_e32 v249, 0x8000, v249
	v_xor_b32_e32 v248, 0x8000, v248
	v_xor_b32_e32 v250, 0x8000, v250
	v_xor_b32_e32 v251, 0x8000, v251
	v_xor_b32_e32 v252, 0x8000, v252
	ds_read_b128 v[180:183], v223
	ds_read_b128 v[184:187], v223 offset:2048
	ds_read_b128 v[188:191], v223 offset:4096
	ds_read_b128 v[192:195], v223 offset:6144
	ds_read_b128 v[212:215], v249
	ds_read_b128 v[218:221], v249 offset:2048
	ds_read_b128 v[224:227], v249 offset:4096
	ds_read_b128 v[228:231], v249 offset:6144
	s_setprio 1
	v_mfma_f32_16x16x32_bf16 v[62:65], v[232:235], v[196:199], v[62:65]
	v_lshl_add_u64 v[140:141], v[136:137], 0, s[8:9]
	v_add_co_u32_e32 v142, vcc, s15, v140
	v_mfma_f32_16x16x32_bf16 v[58:61], v[236:239], v[196:199], v[58:61]
	s_nop 1
	v_addc_co_u32_e32 v143, vcc, 0, v141, vcc
	v_mfma_f32_16x16x32_bf16 v[54:57], v[240:243], v[196:199], v[54:57]
	v_add_co_u32_e32 v144, vcc, s16, v140
	s_nop 1
	v_mfma_f32_16x16x32_bf16 v[50:53], v[244:247], v[196:199], v[50:53]
	v_addc_co_u32_e32 v145, vcc, 0, v141, vcc
	v_add_co_u32_e32 v156, vcc, s17, v140
	v_mfma_f32_16x16x32_bf16 v[46:49], v[232:235], v[200:203], v[46:49]
	s_nop 1
	v_addc_co_u32_e32 v157, vcc, 0, v141, vcc
	v_mfma_f32_16x16x32_bf16 v[42:45], v[236:239], v[200:203], v[42:45]
	v_add_co_u32_e32 v160, vcc, s18, v140
	s_nop 1
	v_mfma_f32_16x16x32_bf16 v[38:41], v[240:243], v[200:203], v[38:41]
	v_addc_co_u32_e32 v161, vcc, 0, v141, vcc
	global_load_dwordx4 v[140:143], v[142:143], off offset:128
	v_mfma_f32_16x16x32_bf16 v[34:37], v[244:247], v[200:203], v[34:37]
	global_load_dwordx4 v[152:155], v[144:145], off offset:128
	global_load_dwordx4 v[156:159], v[156:157], off offset:128
	global_load_dwordx4 v[160:163], v[160:161], off offset:128
	v_mfma_f32_16x16x32_bf16 v[30:33], v[232:235], v[204:207], v[30:33]
	v_lshl_add_u64 v[144:145], v[138:139], 0, s[8:9]
	v_add_co_u32_e32 v164, vcc, s19, v144
	v_mfma_f32_16x16x32_bf16 v[26:29], v[236:239], v[204:207], v[26:29]
	s_nop 1
	v_addc_co_u32_e32 v165, vcc, 0, v145, vcc
	v_mfma_f32_16x16x32_bf16 v[22:25], v[240:243], v[204:207], v[22:25]
	v_add_co_u32_e32 v168, vcc, s20, v144
	s_nop 1
	v_mfma_f32_16x16x32_bf16 v[18:21], v[244:247], v[204:207], v[18:21]
	v_addc_co_u32_e32 v169, vcc, 0, v145, vcc
	v_add_co_u32_e32 v172, vcc, s21, v144
	v_mfma_f32_16x16x32_bf16 v[14:17], v[232:235], v[208:211], v[14:17]
	s_nop 1
	v_addc_co_u32_e32 v173, vcc, 0, v145, vcc
	v_mfma_f32_16x16x32_bf16 v[10:13], v[236:239], v[208:211], v[10:13]
	v_add_co_u32_e32 v144, vcc, s22, v144
	s_nop 1
	v_mfma_f32_16x16x32_bf16 v[6:9], v[240:243], v[208:211], v[6:9]
	v_addc_co_u32_e32 v145, vcc, 0, v145, vcc
	global_load_dwordx4 v[164:167], v[164:165], off offset:128
	v_mfma_f32_16x16x32_bf16 v[2:5], v[244:247], v[208:211], v[2:5]
	global_load_dwordx4 v[168:171], v[168:169], off offset:128
	global_load_dwordx4 v[172:175], v[172:173], off offset:128
	global_load_dwordx4 v[176:179], v[144:145], off offset:128
	s_setprio 0
	s_branch .Lg2_p12_loop

.Lg2_p14_loop:
	ds_read_b128 v[198:201], v214 offset:8192
	ds_read_b128 v[202:205], v214 offset:10240
	ds_read_b128 v[206:209], v214 offset:12288
	ds_read_b128 v[210:213], v214 offset:14336
	s_waitcnt lgkmcnt(4)
	s_setprio 1
	v_mfma_f32_16x16x32_bf16 v[126:129], v[218:221], v[182:185], v[126:129]
	v_mfma_f32_16x16x32_bf16 v[122:125], v[224:227], v[182:185], v[122:125]
	v_mfma_f32_16x16x32_bf16 v[118:121], v[228:231], v[182:185], v[118:121]
	v_mfma_f32_16x16x32_bf16 v[114:117], v[232:235], v[182:185], v[114:117]
	v_mfma_f32_16x16x32_bf16 v[110:113], v[218:221], v[186:189], v[110:113]
	v_mfma_f32_16x16x32_bf16 v[106:109], v[224:227], v[186:189], v[106:109]
	v_mfma_f32_16x16x32_bf16 v[102:105], v[228:231], v[186:189], v[102:105]
	v_mfma_f32_16x16x32_bf16 v[98:101], v[232:235], v[186:189], v[98:101]
	v_mfma_f32_16x16x32_bf16 v[94:97], v[218:221], v[190:193], v[94:97]
	v_mfma_f32_16x16x32_bf16 v[90:93], v[224:227], v[190:193], v[90:93]
	v_mfma_f32_16x16x32_bf16 v[86:89], v[228:231], v[190:193], v[86:89]
	v_mfma_f32_16x16x32_bf16 v[82:85], v[232:235], v[190:193], v[82:85]
	v_mfma_f32_16x16x32_bf16 v[78:81], v[218:221], v[194:197], v[78:81]
	v_mfma_f32_16x16x32_bf16 v[74:77], v[224:227], v[194:197], v[74:77]
	v_mfma_f32_16x16x32_bf16 v[70:73], v[228:231], v[194:197], v[70:73]
	v_mfma_f32_16x16x32_bf16 v[66:69], v[232:235], v[194:197], v[66:69]
	ds_read_b128 v[182:185], v215
	ds_read_b128 v[186:189], v215 offset:2048
	ds_read_b128 v[190:193], v215 offset:4096
	ds_read_b128 v[194:197], v215 offset:6144
	ds_read_b128 v[236:239], v252
	ds_read_b128 v[240:243], v252 offset:2048
	ds_read_b128 v[244:247], v252 offset:4096
	ds_read_b128 v[248:251], v252 offset:6144
	s_waitcnt lgkmcnt(8)
	v_mfma_f32_16x16x32_bf16 v[62:65], v[218:221], v[198:201], v[62:65]
	v_mfma_f32_16x16x32_bf16 v[58:61], v[224:227], v[198:201], v[58:61]
	v_mfma_f32_16x16x32_bf16 v[54:57], v[228:231], v[198:201], v[54:57]
	v_mfma_f32_16x16x32_bf16 v[50:53], v[232:235], v[198:201], v[50:53]
	v_mfma_f32_16x16x32_bf16 v[46:49], v[218:221], v[202:205], v[46:49]
	v_mfma_f32_16x16x32_bf16 v[42:45], v[224:227], v[202:205], v[42:45]
	v_mfma_f32_16x16x32_bf16 v[38:41], v[228:231], v[202:205], v[38:41]
	v_mfma_f32_16x16x32_bf16 v[34:37], v[232:235], v[202:205], v[34:37]
	v_mfma_f32_16x16x32_bf16 v[30:33], v[218:221], v[206:209], v[30:33]
	v_mfma_f32_16x16x32_bf16 v[26:29], v[224:227], v[206:209], v[26:29]
	v_mfma_f32_16x16x32_bf16 v[22:25], v[228:231], v[206:209], v[22:25]
	v_mfma_f32_16x16x32_bf16 v[18:21], v[232:235], v[206:209], v[18:21]
	v_mfma_f32_16x16x32_bf16 v[14:17], v[218:221], v[210:213], v[14:17]
	v_mfma_f32_16x16x32_bf16 v[10:13], v[224:227], v[210:213], v[10:13]
	v_mfma_f32_16x16x32_bf16 v[6:9], v[228:231], v[210:213], v[6:9]
	v_mfma_f32_16x16x32_bf16 v[2:5], v[232:235], v[210:213], v[2:5]
	ds_read_b128 v[198:201], v215 offset:8192
	ds_read_b128 v[202:205], v215 offset:10240
	ds_read_b128 v[206:209], v215 offset:12288
	ds_read_b128 v[210:213], v215 offset:14336
	s_waitcnt lgkmcnt(4)
	v_mfma_f32_16x16x32_bf16 v[126:129], v[236:239], v[182:185], v[126:129]
	v_mfma_f32_16x16x32_bf16 v[122:125], v[240:243], v[182:185], v[122:125]
	s_waitcnt vmcnt(7)
	ds_write_b128 v253, v[150:153]
	v_mfma_f32_16x16x32_bf16 v[118:121], v[244:247], v[182:185], v[118:121]
	v_mfma_f32_16x16x32_bf16 v[114:117], v[248:251], v[182:185], v[114:117]
	s_waitcnt vmcnt(6)
	ds_write_b128 v253, v[154:157] offset:8192
	v_mfma_f32_16x16x32_bf16 v[110:113], v[236:239], v[186:189], v[110:113]
	v_mfma_f32_16x16x32_bf16 v[106:109], v[240:243], v[186:189], v[106:109]
	s_waitcnt vmcnt(5)
	ds_write_b128 v253, v[158:161] offset:16384
	v_mfma_f32_16x16x32_bf16 v[102:105], v[244:247], v[186:189], v[102:105]
	v_mfma_f32_16x16x32_bf16 v[98:101], v[248:251], v[186:189], v[98:101]
	s_waitcnt vmcnt(4)
	ds_write_b128 v253, v[162:165] offset:24576
	v_mfma_f32_16x16x32_bf16 v[94:97], v[236:239], v[190:193], v[94:97]
	v_mfma_f32_16x16x32_bf16 v[90:93], v[240:243], v[190:193], v[90:93]
	s_waitcnt vmcnt(3)
	ds_write_b128 v254, v[166:169]
	v_mfma_f32_16x16x32_bf16 v[86:89], v[244:247], v[190:193], v[86:89]
	v_mfma_f32_16x16x32_bf16 v[82:85], v[248:251], v[190:193], v[82:85]
	s_waitcnt vmcnt(2)
	ds_write_b128 v254, v[170:173] offset:8192
	v_mfma_f32_16x16x32_bf16 v[78:81], v[236:239], v[194:197], v[78:81]
	v_mfma_f32_16x16x32_bf16 v[74:77], v[240:243], v[194:197], v[74:77]
	s_waitcnt vmcnt(1)
	ds_write_b128 v254, v[174:177] offset:16384
	v_mfma_f32_16x16x32_bf16 v[70:73], v[244:247], v[194:197], v[70:73]
	v_mfma_f32_16x16x32_bf16 v[66:69], v[248:251], v[194:197], v[66:69]
	s_waitcnt vmcnt(0)
	ds_write_b128 v254, v[178:181] offset:24576
	s_setprio 0
	s_waitcnt lgkmcnt(0)
	s_barrier
	s_add_u32 s0, s0, 0x80
	s_addc_u32 s1, s1, 0
	s_cmpk_eq_i32 s0, 0x780
	s_cbranch_scc1 .Lg2_p14_tail
	v_xor_b32_e32 v214, 0x8000, v214
	v_xor_b32_e32 v223, 0x8000, v223
	v_xor_b32_e32 v215, 0x8000, v215
	v_xor_b32_e32 v252, 0x8000, v252
	v_xor_b32_e32 v253, 0x8000, v253
	v_xor_b32_e32 v254, 0x8000, v254
	ds_read_b128 v[182:185], v214
	ds_read_b128 v[186:189], v214 offset:2048
	ds_read_b128 v[190:193], v214 offset:4096
	ds_read_b128 v[194:197], v214 offset:6144
	ds_read_b128 v[218:221], v223
	ds_read_b128 v[224:227], v223 offset:2048
	ds_read_b128 v[228:231], v223 offset:4096
	ds_read_b128 v[232:235], v223 offset:6144
	s_setprio 1
	v_mfma_f32_16x16x32_bf16 v[62:65], v[236:239], v[198:201], v[62:65]
	v_lshl_add_u64 v[150:151], v[142:143], 0, s[0:1]
	v_add_co_u32_e32 v152, vcc, s12, v150
	v_mfma_f32_16x16x32_bf16 v[58:61], v[240:243], v[198:201], v[58:61]
	s_nop 1
	v_addc_co_u32_e32 v153, vcc, 0, v151, vcc
	v_mfma_f32_16x16x32_bf16 v[54:57], v[244:247], v[198:201], v[54:57]
	v_add_co_u32_e32 v154, vcc, s13, v150
	s_nop 1
	v_mfma_f32_16x16x32_bf16 v[50:53], v[248:251], v[198:201], v[50:53]
	v_addc_co_u32_e32 v155, vcc, 0, v151, vcc
	v_add_co_u32_e32 v158, vcc, s14, v150
	v_mfma_f32_16x16x32_bf16 v[46:49], v[236:239], v[202:205], v[46:49]
	s_nop 1
	v_addc_co_u32_e32 v159, vcc, 0, v151, vcc
	v_mfma_f32_16x16x32_bf16 v[42:45], v[240:243], v[202:205], v[42:45]
	v_add_co_u32_e32 v162, vcc, s15, v150
	s_nop 1
	v_mfma_f32_16x16x32_bf16 v[38:41], v[244:247], v[202:205], v[38:41]
	v_addc_co_u32_e32 v163, vcc, 0, v151, vcc
	global_load_dwordx4 v[150:153], v[152:153], off offset:128
	v_mfma_f32_16x16x32_bf16 v[34:37], v[248:251], v[202:205], v[34:37]
	global_load_dwordx4 v[154:157], v[154:155], off offset:128
	global_load_dwordx4 v[158:161], v[158:159], off offset:128
	global_load_dwordx4 v[162:165], v[162:163], off offset:128
	v_mfma_f32_16x16x32_bf16 v[30:33], v[236:239], v[206:209], v[30:33]
	v_lshl_add_u64 v[174:175], v[140:141], 0, s[0:1]
	v_add_co_u32_e32 v166, vcc, s16, v174
	v_mfma_f32_16x16x32_bf16 v[26:29], v[240:243], v[206:209], v[26:29]
	s_nop 1
	v_addc_co_u32_e32 v167, vcc, 0, v175, vcc
	v_mfma_f32_16x16x32_bf16 v[22:25], v[244:247], v[206:209], v[22:25]
	v_add_co_u32_e32 v170, vcc, s17, v174
	s_nop 1
	v_mfma_f32_16x16x32_bf16 v[18:21], v[248:251], v[206:209], v[18:21]
	v_addc_co_u32_e32 v171, vcc, 0, v175, vcc
	v_add_co_u32_e32 v176, vcc, s18, v174
	v_mfma_f32_16x16x32_bf16 v[14:17], v[236:239], v[210:213], v[14:17]
	s_nop 1
	v_addc_co_u32_e32 v177, vcc, 0, v175, vcc
	v_mfma_f32_16x16x32_bf16 v[10:13], v[240:243], v[210:213], v[10:13]
	v_add_co_u32_e32 v178, vcc, s19, v174
	s_nop 1
	v_mfma_f32_16x16x32_bf16 v[6:9], v[244:247], v[210:213], v[6:9]
	v_addc_co_u32_e32 v179, vcc, 0, v175, vcc
	global_load_dwordx4 v[166:169], v[166:167], off offset:128
	v_mfma_f32_16x16x32_bf16 v[2:5], v[248:251], v[210:213], v[2:5]
	global_load_dwordx4 v[170:173], v[170:171], off offset:128
	global_load_dwordx4 v[174:177], v[176:177], off offset:128
	global_load_dwordx4 v[178:181], v[178:179], off offset:128
	s_setprio 0
	s_branch .Lg2_p14_loop

.Lg2_p15_loop:
	ds_read_b128 v[196:199], v223 offset:8192
	ds_read_b128 v[200:203], v223 offset:10240
	ds_read_b128 v[204:207], v223 offset:12288
	ds_read_b128 v[208:211], v223 offset:14336
	s_waitcnt lgkmcnt(4)
	s_setprio 1
	v_mfma_f32_16x16x32_bf16 v[126:129], v[212:215], v[180:183], v[126:129]
	v_mfma_f32_16x16x32_bf16 v[122:125], v[218:221], v[180:183], v[122:125]
	v_mfma_f32_16x16x32_bf16 v[118:121], v[224:227], v[180:183], v[118:121]
	v_mfma_f32_16x16x32_bf16 v[114:117], v[228:231], v[180:183], v[114:117]
	v_mfma_f32_16x16x32_bf16 v[110:113], v[212:215], v[184:187], v[110:113]
	v_mfma_f32_16x16x32_bf16 v[106:109], v[218:221], v[184:187], v[106:109]
	v_mfma_f32_16x16x32_bf16 v[102:105], v[224:227], v[184:187], v[102:105]
	v_mfma_f32_16x16x32_bf16 v[98:101], v[228:231], v[184:187], v[98:101]
	v_mfma_f32_16x16x32_bf16 v[94:97], v[212:215], v[188:191], v[94:97]
	v_mfma_f32_16x16x32_bf16 v[90:93], v[218:221], v[188:191], v[90:93]
	v_mfma_f32_16x16x32_bf16 v[86:89], v[224:227], v[188:191], v[86:89]
	v_mfma_f32_16x16x32_bf16 v[82:85], v[228:231], v[188:191], v[82:85]
	v_mfma_f32_16x16x32_bf16 v[78:81], v[212:215], v[192:195], v[78:81]
	v_mfma_f32_16x16x32_bf16 v[74:77], v[218:221], v[192:195], v[74:77]
	v_mfma_f32_16x16x32_bf16 v[70:73], v[224:227], v[192:195], v[70:73]
	v_mfma_f32_16x16x32_bf16 v[66:69], v[228:231], v[192:195], v[66:69]
	ds_read_b128 v[180:183], v248
	ds_read_b128 v[184:187], v248 offset:2048
	ds_read_b128 v[188:191], v248 offset:4096
	ds_read_b128 v[192:195], v248 offset:6144
	ds_read_b128 v[232:235], v250
	ds_read_b128 v[236:239], v250 offset:2048
	ds_read_b128 v[240:243], v250 offset:4096
	ds_read_b128 v[244:247], v250 offset:6144
	s_waitcnt lgkmcnt(8)
	v_mfma_f32_16x16x32_bf16 v[62:65], v[212:215], v[196:199], v[62:65]
	v_mfma_f32_16x16x32_bf16 v[58:61], v[218:221], v[196:199], v[58:61]
	v_mfma_f32_16x16x32_bf16 v[54:57], v[224:227], v[196:199], v[54:57]
	v_mfma_f32_16x16x32_bf16 v[50:53], v[228:231], v[196:199], v[50:53]
	v_mfma_f32_16x16x32_bf16 v[46:49], v[212:215], v[200:203], v[46:49]
	v_mfma_f32_16x16x32_bf16 v[42:45], v[218:221], v[200:203], v[42:45]
	v_mfma_f32_16x16x32_bf16 v[38:41], v[224:227], v[200:203], v[38:41]
	v_mfma_f32_16x16x32_bf16 v[34:37], v[228:231], v[200:203], v[34:37]
	v_mfma_f32_16x16x32_bf16 v[30:33], v[212:215], v[204:207], v[30:33]
	v_mfma_f32_16x16x32_bf16 v[26:29], v[218:221], v[204:207], v[26:29]
	v_mfma_f32_16x16x32_bf16 v[22:25], v[224:227], v[204:207], v[22:25]
	v_mfma_f32_16x16x32_bf16 v[18:21], v[228:231], v[204:207], v[18:21]
	v_mfma_f32_16x16x32_bf16 v[14:17], v[212:215], v[208:211], v[14:17]
	v_mfma_f32_16x16x32_bf16 v[10:13], v[218:221], v[208:211], v[10:13]
	v_mfma_f32_16x16x32_bf16 v[6:9], v[224:227], v[208:211], v[6:9]
	v_mfma_f32_16x16x32_bf16 v[2:5], v[228:231], v[208:211], v[2:5]
	ds_read_b128 v[196:199], v248 offset:8192
	ds_read_b128 v[200:203], v248 offset:10240
	ds_read_b128 v[204:207], v248 offset:12288
	ds_read_b128 v[208:211], v248 offset:14336
	s_waitcnt lgkmcnt(4)
	v_mfma_f32_16x16x32_bf16 v[126:129], v[232:235], v[180:183], v[126:129]
	v_mfma_f32_16x16x32_bf16 v[122:125], v[236:239], v[180:183], v[122:125]
	s_waitcnt vmcnt(7)
	ds_write_b128 v251, v[140:143]
	v_mfma_f32_16x16x32_bf16 v[118:121], v[240:243], v[180:183], v[118:121]
	v_mfma_f32_16x16x32_bf16 v[114:117], v[244:247], v[180:183], v[114:117]
	s_waitcnt vmcnt(6)
	ds_write_b128 v251, v[152:155] offset:8192
	v_mfma_f32_16x16x32_bf16 v[110:113], v[232:235], v[184:187], v[110:113]
	v_mfma_f32_16x16x32_bf16 v[106:109], v[236:239], v[184:187], v[106:109]
	s_waitcnt vmcnt(5)
	ds_write_b128 v251, v[156:159] offset:16384
	v_mfma_f32_16x16x32_bf16 v[102:105], v[240:243], v[184:187], v[102:105]
	v_mfma_f32_16x16x32_bf16 v[98:101], v[244:247], v[184:187], v[98:101]
	s_waitcnt vmcnt(4)
	ds_write_b128 v251, v[160:163] offset:24576
	v_mfma_f32_16x16x32_bf16 v[94:97], v[232:235], v[188:191], v[94:97]
	v_mfma_f32_16x16x32_bf16 v[90:93], v[236:239], v[188:191], v[90:93]
	s_waitcnt vmcnt(3)
	ds_write_b128 v252, v[164:167]
	v_mfma_f32_16x16x32_bf16 v[86:89], v[240:243], v[188:191], v[86:89]
	v_mfma_f32_16x16x32_bf16 v[82:85], v[244:247], v[188:191], v[82:85]
	s_waitcnt vmcnt(2)
	ds_write_b128 v252, v[168:171] offset:8192
	v_mfma_f32_16x16x32_bf16 v[78:81], v[232:235], v[192:195], v[78:81]
	v_mfma_f32_16x16x32_bf16 v[74:77], v[236:239], v[192:195], v[74:77]
	s_waitcnt vmcnt(1)
	ds_write_b128 v252, v[172:175] offset:16384
	v_mfma_f32_16x16x32_bf16 v[70:73], v[240:243], v[192:195], v[70:73]
	v_mfma_f32_16x16x32_bf16 v[66:69], v[244:247], v[192:195], v[66:69]
	s_waitcnt vmcnt(0)
	ds_write_b128 v252, v[176:179] offset:24576
	s_setprio 0
	s_waitcnt lgkmcnt(0)
	s_barrier
	s_add_u32 s8, s8, 0x80
	s_addc_u32 s9, s9, 0
	s_cmpk_eq_i32 s8, 0x1580
	s_cbranch_scc1 .Lg2_p15_tail
	v_xor_b32_e32 v223, 0x8000, v223
	v_xor_b32_e32 v249, 0x8000, v249
	v_xor_b32_e32 v248, 0x8000, v248
	v_xor_b32_e32 v250, 0x8000, v250
	v_xor_b32_e32 v251, 0x8000, v251
	v_xor_b32_e32 v252, 0x8000, v252
	ds_read_b128 v[180:183], v223
	ds_read_b128 v[184:187], v223 offset:2048
	ds_read_b128 v[188:191], v223 offset:4096
	ds_read_b128 v[192:195], v223 offset:6144
	ds_read_b128 v[212:215], v249
	ds_read_b128 v[218:221], v249 offset:2048
	ds_read_b128 v[224:227], v249 offset:4096
	ds_read_b128 v[228:231], v249 offset:6144
	s_setprio 1
	v_mfma_f32_16x16x32_bf16 v[62:65], v[232:235], v[196:199], v[62:65]
	v_lshl_add_u64 v[140:141], v[136:137], 0, s[8:9]
	v_add_co_u32_e32 v142, vcc, s16, v140
	v_mfma_f32_16x16x32_bf16 v[58:61], v[236:239], v[196:199], v[58:61]
	s_nop 1
	v_addc_co_u32_e32 v143, vcc, 0, v141, vcc
	v_mfma_f32_16x16x32_bf16 v[54:57], v[240:243], v[196:199], v[54:57]
	v_add_co_u32_e32 v144, vcc, s17, v140
	s_nop 1
	v_mfma_f32_16x16x32_bf16 v[50:53], v[244:247], v[196:199], v[50:53]
	v_addc_co_u32_e32 v145, vcc, 0, v141, vcc
	v_add_co_u32_e32 v156, vcc, s18, v140
	v_mfma_f32_16x16x32_bf16 v[46:49], v[232:235], v[200:203], v[46:49]
	s_nop 1
	v_addc_co_u32_e32 v157, vcc, 0, v141, vcc
	v_mfma_f32_16x16x32_bf16 v[42:45], v[236:239], v[200:203], v[42:45]
	v_add_co_u32_e32 v160, vcc, s19, v140
	s_nop 1
	v_mfma_f32_16x16x32_bf16 v[38:41], v[240:243], v[200:203], v[38:41]
	v_addc_co_u32_e32 v161, vcc, 0, v141, vcc
	global_load_dwordx4 v[140:143], v[142:143], off offset:128
	v_mfma_f32_16x16x32_bf16 v[34:37], v[244:247], v[200:203], v[34:37]
	global_load_dwordx4 v[152:155], v[144:145], off offset:128
	global_load_dwordx4 v[156:159], v[156:157], off offset:128
	global_load_dwordx4 v[160:163], v[160:161], off offset:128
	v_mfma_f32_16x16x32_bf16 v[30:33], v[232:235], v[204:207], v[30:33]
	v_lshl_add_u64 v[144:145], v[138:139], 0, s[8:9]
	v_add_co_u32_e32 v164, vcc, s20, v144
	v_mfma_f32_16x16x32_bf16 v[26:29], v[236:239], v[204:207], v[26:29]
	s_nop 1
	v_addc_co_u32_e32 v165, vcc, 0, v145, vcc
	v_mfma_f32_16x16x32_bf16 v[22:25], v[240:243], v[204:207], v[22:25]
	v_add_co_u32_e32 v168, vcc, s21, v144
	s_nop 1
	v_mfma_f32_16x16x32_bf16 v[18:21], v[244:247], v[204:207], v[18:21]
	v_addc_co_u32_e32 v169, vcc, 0, v145, vcc
	v_add_co_u32_e32 v172, vcc, s22, v144
	v_mfma_f32_16x16x32_bf16 v[14:17], v[232:235], v[208:211], v[14:17]
	s_nop 1
	v_addc_co_u32_e32 v173, vcc, 0, v145, vcc
	v_mfma_f32_16x16x32_bf16 v[10:13], v[236:239], v[208:211], v[10:13]
	v_add_co_u32_e32 v144, vcc, s23, v144
	s_nop 1
	v_mfma_f32_16x16x32_bf16 v[6:9], v[240:243], v[208:211], v[6:9]
	v_addc_co_u32_e32 v145, vcc, 0, v145, vcc
	global_load_dwordx4 v[164:167], v[164:165], off offset:128
	v_mfma_f32_16x16x32_bf16 v[2:5], v[244:247], v[208:211], v[2:5]
	global_load_dwordx4 v[168:171], v[168:169], off offset:128
	global_load_dwordx4 v[172:175], v[172:173], off offset:128
	global_load_dwordx4 v[176:179], v[144:145], off offset:128
	s_setprio 0
	s_branch .Lg2_p15_loop
